# one static s_setprio 1 at kernel entry for waves 4-7 (younger half), kernel-wide
# baseline (speedup 1.0000x reference)
; #define LAS __attribute__((address_space(3)))
; __device__ __forceinline__ unsigned xb_add(unsigned* p, unsigned v) { return __hip_atomic_fetch_add(p, v, __ATOMIC_RELAXED, __HIP_MEMORY_SCOPE_AGENT); }
; __device__ __forceinline__ unsigned xb_xcc_id() { return (unsigned)__builtin_amdgcn_s_getreg((3 << 11) | 20) & 0xFu; }
; __device__ __forceinline__ XcdBarrier xcd_barrier_post(unsigned* bar, volatile LAS unsigned* st) {
;     XcdBarrier b; b.bar = bar; b.x = xb_xcc_id(); b.st = st;
;     if (threadIdx.x == 0) (void)xb_add(&bar[XB_XCNT(b.x)], 1u);
;     return b;
; }
; __global__ void __launch_bounds__(512, 2) mk_fwd(Args a) {
;     ...
;     volatile LAS unsigned* xst = (volatile LAS unsigned*)(llds + (LDS_BYTES - 16));
;     if (threadIdx.x < 4) xst[threadIdx.x] = 0u;
;     __syncthreads();
;     { GV(); (void)xcd_barrier_post((unsigned*)(ws + WS_CTL), xst); (void)xcd_barrier_post((unsigned*)(ws + WS_CTL) + (1 + grp) * 4096, xst + 2); }
_ZN2mk6mk_fwdENS_4ArgsE:
	v_readfirstlane_b32 s98, v0
	s_nop 3
	s_and_b32 s98, s98, 0x3ff
	s_lshr_b32 s98, s98, 6
	s_cmp_ge_u32 s98, 4
	s_cbranch_scc0 .Lprio_done
	s_setprio 1
.Lprio_done:
	s_load_dwordx16 s[76:91], s[0:1], 0x80
	s_load_dword s33, s[0:1], 0xc8
	s_mov_b32 s93, s2
	s_add_u32 s2, s0, 0xc8
	v_and_b32_e32 v181, 0x3ff, v0
	s_addc_u32 s3, s1, 0
	v_cmp_gt_u32_e32 vcc, 4, v181
	s_and_saveexec_b64 s[4:5], vcc
	v_lshl_add_u32 v1, v181, 2, 0
	v_add_u32_e32 v1, 0x24800, v1
	v_mov_b32_e32 v2, 0
	ds_write_b32 v1, v2
	s_or_b64 exec, exec, s[4:5]
	s_mov_b32 s10, s93
	s_waitcnt lgkmcnt(0)
	s_add_u32 s22, s90, 0x1f800000
	s_barrier
	s_addc_u32 s23, s91, 0
	s_getreg_b32 s11, hwreg(HW_REG_XCC_ID, 0, 4)
	v_cmp_eq_u32_e64 s[66:67], 0, v181
	v_cmp_ne_u32_e32 vcc, 0, v181
	s_and_saveexec_b64 s[4:5], vcc
	s_xor_b64 s[4:5], exec, s[4:5]
	s_getreg_b32 s6, hwreg(HW_REG_XCC_ID, 0, 4)
	s_andn2_saveexec_b64 s[4:5], s[4:5]
	s_cbranch_execz .LBB0_10
	s_mov_b64 s[8:9], exec
	v_mbcnt_lo_u32_b32 v1, s8, 0
	v_mbcnt_hi_u32_b32 v1, s9, v1
	v_cmp_eq_u32_e32 vcc, 0, v1
	s_and_saveexec_b64 s[6:7], vcc
	s_cbranch_execz .LBB0_7
	s_lshl_b32 s11, s11, 8
	s_and_b32 s11, s11, 0xf00
	s_bcnt1_i32_b64 s8, s[8:9]
	v_mov_b32_e32 v1, s11
	v_mov_b32_e32 v2, s8
	global_atomic_add v1, v2, s[22:23] offset:1024
